# flat2global P2 setup: the 6 flat_load_dword of the P2 item setup issued as global loads
# speedup vs baseline: 1.0039x; 1.0003x over previous
; __device__ __forceinline__ int lane_id() { return (int)__builtin_amdgcn_mbcnt_hi(~0u, __builtin_amdgcn_mbcnt_lo(~0u, 0u)); }
; __global__ void __launch_bounds__(NWAVES * 64, 2) fwd(Args args) {
;     ...
;     if (IN(2)) {
;         unsigned char* wsp = ws; asm volatile("" : "+s"(wsp)); const unsigned char* tbl = wsp + WS_PTRS;
;         const float* ret_gn = ld_uptr(tbl, 4); const float* diff_qn = ld_uptr(tbl, 5); const float* diff_kn = ld_uptr(tbl, 6); const float* lq1 = ld_uptr(tbl, 7); const float* lk1 = ld_uptr(tbl, 8);
;         const float* lq2 = ld_uptr(tbl, 9); const float* lk2 = ld_uptr(tbl, 10); const float* subln = ld_uptr(tbl, 11);
;         bf16_t* Z = (bf16_t*)(wsp + WS_Z); bf16_t* MIX = (bf16_t*)(wsp + WS_MIX);
;         int lane2 = lane_id(); asm volatile("" : "+v"(lane2));
;         const float d1 = wave_sum(lq1[lane2] * lk1[lane2]), d2 = wave_sum(lq2[lane2] * lk2[lane2]);
;         float lam; { float lv = __expf(d1) - __expf(d2) + 0.2f; asm volatile("" : "+v"(lv)); lam = __uint_as_float(__builtin_amdgcn_readfirstlane(__float_as_uint(lv))); }
;         const float mq = wave_max(fabsf(diff_qn[lane2])), mk = wave_max(fabsf(diff_kn[lane2]));
;         float shift; { float sv = 11.541560327111707f * mq * mk; asm volatile("" : "+v"(sv)); shift = __uint_as_float(__builtin_amdgcn_readfirstlane(__float_as_uint(sv))); }
.LBB0_561:
	s_cmp_lt_i32 s82, 3
	s_cselect_b64 s[2:3], -1, 0
	v_writelane_b32 v254, s2, 2
	s_and_b64 s[0:1], s[2:3], s[0:1]
	s_andn2_b64 vcc, exec, s[0:1]
	v_writelane_b32 v254, s3, 3
	s_cbranch_vccnz .LBB0_654
	v_writelane_b32 v254, s96, 4
	v_mov_b32_e32 v181, 0
	v_mbcnt_lo_u32_b32 v13, -1, 0
	v_writelane_b32 v254, s97, 5
	v_writelane_b32 v254, s94, 6
	v_writelane_b32 v254, s93, 7
	v_writelane_b32 v254, s92, 8
	v_writelane_b32 v254, s90, 9
	v_mbcnt_hi_u32_b32 v183, -1, v13
	v_mov_b32_e32 v12, 0x20000
	v_writelane_b32 v254, s91, 10
	v_writelane_b32 v254, s87, 11
	v_writelane_b32 v254, s88, 12
	v_mov_b32_e32 v16, v183
	s_mov_b32 s27, 0
	v_writelane_b32 v254, s89, 13
	v_writelane_b32 v254, s86, 14
	v_writelane_b32 v254, s84, 15
	s_nop 1
	v_writelane_b32 v254, s85, 16
	v_writelane_b32 v254, s79, 17
	v_writelane_b32 v254, s77, 18
	v_writelane_b32 v254, s80, 19
	s_mov_b64 s[0:1], s[80:81]
	s_add_u32 s2, s0, 0x20020
	s_addc_u32 s3, s1, 0
	global_load_dwordx4 v[0:3], v181, s[2:3] offset:16
	global_load_dwordx4 v[4:7], v181, s[2:3] offset:32
	global_load_dwordx4 v[8:11], v181, s[2:3] offset:48
	v_writelane_b32 v254, s81, 20
	global_load_dwordx4 v[12:15], v12, s[0:1] offset:32
	v_writelane_b32 v254, s82, 21
	v_ashrrev_i32_e32 v17, 31, v16
	v_lshlrev_b64 v[16:17], 2, v[16:17]
	v_writelane_b32 v254, s83, 22
	s_cmpk_gt_i32 s95, 0xff
	s_waitcnt vmcnt(0)
	v_readfirstlane_b32 s3, v3
	v_readfirstlane_b32 s2, v2
	v_readfirstlane_b32 s5, v5
	v_readfirstlane_b32 s4, v4
	v_readfirstlane_b32 s7, v7
	v_readfirstlane_b32 s6, v6
	v_readfirstlane_b32 s9, v9
	v_readfirstlane_b32 s8, v8
	v_lshl_add_u64 v[2:3], s[2:3], 0, v[16:17]
	v_lshl_add_u64 v[4:5], s[4:5], 0, v[16:17]
	v_lshl_add_u64 v[6:7], s[6:7], 0, v[16:17]
	v_lshl_add_u64 v[8:9], s[8:9], 0, v[16:17]
	global_load_dword v18, v[2:3], off
	global_load_dword v19, v[4:5], off
	global_load_dword v20, v[6:7], off
	global_load_dword v21, v[8:9], off
	v_and_b32_e32 v2, 64, v183
	v_xor_b32_e32 v3, 1, v183
	v_add_u32_e32 v2, 64, v2
	v_cmp_lt_i32_e32 vcc, v3, v2
	v_xor_b32_e32 v4, 2, v183
	v_xor_b32_e32 v5, 4, v183
	v_cndmask_b32_e32 v3, v183, v3, vcc
	v_lshlrev_b32_e32 v9, 2, v3
	v_cmp_lt_i32_e32 vcc, v4, v2
	v_xor_b32_e32 v6, 8, v183
	v_xor_b32_e32 v7, 16, v183
	v_cndmask_b32_e32 v4, v183, v4, vcc
	v_lshlrev_b32_e32 v4, 2, v4
	v_cmp_lt_i32_e32 vcc, v5, v2
	v_xor_b32_e32 v8, 32, v183
	v_readfirstlane_b32 s5, v1
	v_cndmask_b32_e32 v5, v183, v5, vcc
	v_lshlrev_b32_e32 v5, 2, v5
	v_cmp_lt_i32_e32 vcc, v6, v2
	v_readfirstlane_b32 s3, v15
	v_readfirstlane_b32 s2, v14
	v_cndmask_b32_e32 v6, v183, v6, vcc
	v_lshlrev_b32_e32 v6, 2, v6
	v_cmp_lt_i32_e32 vcc, v7, v2
	v_readfirstlane_b32 s4, v0
	v_readfirstlane_b32 s85, v11
	v_cndmask_b32_e32 v7, v183, v7, vcc
	v_lshlrev_b32_e32 v7, 2, v7
	v_cmp_lt_i32_e32 vcc, v8, v2
	v_readfirstlane_b32 s84, v10
	s_waitcnt vmcnt(0) lgkmcnt(0)
	v_mul_f32_e32 v3, v18, v19
	ds_bpermute_b32 v3, v9, v3
	v_mul_f32_e32 v22, v20, v21
	ds_bpermute_b32 v22, v9, v22
	v_cndmask_b32_e32 v2, v183, v8, vcc
	v_lshlrev_b32_e32 v8, 2, v2
	s_waitcnt lgkmcnt(1)
	v_fmac_f32_e32 v3, v18, v19
	ds_bpermute_b32 v18, v4, v3
	s_waitcnt lgkmcnt(1)
	v_fmac_f32_e32 v22, v20, v21
	ds_bpermute_b32 v19, v4, v22
	s_waitcnt lgkmcnt(1)
	v_add_f32_e32 v3, v3, v18
	s_waitcnt lgkmcnt(0)
	v_add_f32_e32 v18, v22, v19
	ds_bpermute_b32 v19, v5, v3
	ds_bpermute_b32 v20, v5, v18
	s_waitcnt lgkmcnt(1)
	v_add_f32_e32 v3, v3, v19
	s_waitcnt lgkmcnt(0)
	v_add_f32_e32 v18, v18, v20
	ds_bpermute_b32 v19, v6, v3
	ds_bpermute_b32 v20, v6, v18
	s_waitcnt lgkmcnt(1)
	v_add_f32_e32 v3, v3, v19
	s_waitcnt lgkmcnt(0)
	v_add_f32_e32 v18, v18, v20
	ds_bpermute_b32 v19, v7, v3
	ds_bpermute_b32 v20, v7, v18
	s_waitcnt lgkmcnt(1)
	v_add_f32_e32 v2, v3, v19
	s_waitcnt lgkmcnt(0)
	v_add_f32_e32 v3, v18, v20
	ds_bpermute_b32 v18, v8, v2
	ds_bpermute_b32 v19, v8, v3
	s_waitcnt lgkmcnt(1)
	v_add_f32_e32 v1, v2, v18
	s_waitcnt lgkmcnt(0)
	v_add_f32_e32 v2, v3, v19
	v_mul_f32_e32 v1, 0x3fb8aa3b, v1
	v_mul_f32_e32 v2, 0x3fb8aa3b, v2
	v_exp_f32_e32 v14, v1
	v_exp_f32_e32 v15, v2
	v_lshl_add_u64 v[0:1], s[2:3], 0, v[16:17]
	v_lshl_add_u64 v[2:3], s[4:5], 0, v[16:17]
	v_readfirstlane_b32 s2, v13
	v_sub_f32_e32 v14, v14, v15
	v_add_f32_e32 v14, 0x3e4ccccd, v14
	global_load_dword v15, v[0:1], off
	global_load_dword v16, v[2:3], off
	v_writelane_b32 v254, s2, 23
	v_readfirstlane_b32 s2, v12
	v_readfirstlane_b32 s28, v14
	s_waitcnt vmcnt(0) lgkmcnt(0)
	v_and_b32_e32 v0, 0x7fffffff, v15
	v_and_b32_e32 v1, 0x7fffffff, v16
	ds_bpermute_b32 v0, v9, v0
	ds_bpermute_b32 v1, v9, v1
	v_max_f32_e64 v2, |v15|, |v15|
	v_max_f32_e64 v3, |v16|, |v16|
	v_writelane_b32 v254, s2, 24
	s_waitcnt lgkmcnt(1)
	v_max_f32_e32 v0, v0, v0
	s_waitcnt lgkmcnt(0)
	v_max_f32_e32 v1, v1, v1
	v_max_f32_e32 v0, v2, v0
	v_max_f32_e32 v1, v3, v1
	ds_bpermute_b32 v2, v4, v0
	ds_bpermute_b32 v3, v4, v1
	s_waitcnt lgkmcnt(1)
	v_max_f32_e32 v2, v2, v2
	s_waitcnt lgkmcnt(0)
	v_max_f32_e32 v3, v3, v3
	v_max_f32_e32 v0, v0, v2
	v_max_f32_e32 v1, v1, v3
	ds_bpermute_b32 v2, v5, v0
	ds_bpermute_b32 v3, v5, v1
	s_waitcnt lgkmcnt(1)
	v_max_f32_e32 v2, v2, v2
	s_waitcnt lgkmcnt(0)
	v_max_f32_e32 v3, v3, v3
	v_max_f32_e32 v0, v0, v2
	v_max_f32_e32 v1, v1, v3
	ds_bpermute_b32 v2, v6, v0
	ds_bpermute_b32 v3, v6, v1
	s_waitcnt lgkmcnt(1)
	v_max_f32_e32 v2, v2, v2
	s_waitcnt lgkmcnt(0)
	v_max_f32_e32 v3, v3, v3
	v_max_f32_e32 v0, v0, v2
	v_max_f32_e32 v1, v1, v3
	ds_bpermute_b32 v2, v7, v0
	ds_bpermute_b32 v3, v7, v1
	s_waitcnt lgkmcnt(1)
	v_max_f32_e32 v2, v2, v2
	s_waitcnt lgkmcnt(0)
	v_max_f32_e32 v3, v3, v3
	v_max_f32_e32 v0, v0, v2
	v_max_f32_e32 v1, v1, v3
	ds_bpermute_b32 v2, v8, v0
	ds_bpermute_b32 v3, v8, v1
	s_waitcnt lgkmcnt(1)
	v_max_f32_e32 v2, v2, v2
	s_waitcnt lgkmcnt(0)
	v_max_f32_e32 v3, v3, v3
	v_max_f32_e32 v0, v0, v2
	v_max_f32_e32 v1, v1, v3
	v_mul_f32_e32 v0, 0x4138aa3b, v0
	v_mul_f32_e32 v0, v0, v1
	s_nop 0
	v_readfirstlane_b32 s2, v0
	s_cbranch_scc1 .LBB0_653
; template <bool DIFF>
; __device__ __forceinline__ void attn_item(LAS unsigned char* lds, const bf16_t* Z, bf16_t* MIX, int b, int h, int t, float lam, float shift, const float* gain, int tid, int wid, int lane) {
;     ...
;     const char* kbase = (const char*)(Z + (size_t)(b * SEQ) * DIN + kcol);
;     const char* vbase = (const char*)(Z + (size_t)(b * SEQ) * DIN + vcol);
;     const unsigned krow = (unsigned)(8 * wid + (lane >> 3));
;     const unsigned kso = (krow * DIN + 8u * ((unsigned)(lane & 7) ^ (krow & 7u))) * 2u;
;     const unsigned vrow = (unsigned)(4 * wid + (lane >> 4));
;     const unsigned vso = (vrow * DIN + 8u * (2u * ((((unsigned)lane & 15u) >> 1) ^ (vrow & 7u)) + ((unsigned)lane & 1u))) * 2u;
; __global__ void __launch_bounds__(NWAVES * 64, 2) fwd(Args args) {
;     ...
;         for (int pi = vcu; pi < 256; pi += G) {
;             const int bh = pi >> 3, tp = pi & 7, b = bh >> 3, h = bh & 7;
;             attn_item<true>(lds, Z, MIX, b, h, 15 - tp, lam, shift, subln, 0, wid, 0);
	s_add_u32 s30, s0, 0x5300000
	s_addc_u32 s31, s1, 0
	s_add_u32 s88, s0, 0x2f00000
	s_addc_u32 s89, s1, 0
	s_lshl_b32 s29, s60, 4
	s_lshl_b32 s34, s60, 3
	s_lshl_b32 s35, s60, 2
	s_add_i32 s90, s33, 0
	v_sub_f32_e64 v0, 0, s2
	s_add_u32 s2, s0, 0x54c2800
	v_writelane_b32 v254, s2, 25
	s_addc_u32 s2, s1, 0
	v_writelane_b32 v254, s2, 26
	s_lshl_b32 s2, s95, 5
	s_lshl_b32 s3, s78, 5
	v_writelane_b32 v254, s3, 27
	s_add_u32 s3, s0, 0x54c0800
	v_writelane_b32 v254, s3, 28
	s_addc_u32 s3, s1, 0
	v_writelane_b32 v254, s3, 29
	s_add_u32 s0, s0, 0x54c0400
	v_writelane_b32 v254, s0, 30
	s_addc_u32 s0, s1, 0
	v_writelane_b32 v254, s0, 31
	v_writelane_b32 v254, s78, 32
	v_writelane_b32 v254, s66, 33
	v_writelane_b32 v254, s84, 34
	s_add_i32 s17, s90, 0x2000
	s_add_i32 s38, s90, 0x6000
	v_writelane_b32 v254, s85, 35
	v_writelane_b32 v254, s28, 36
	v_writelane_b32 v254, s30, 37
	s_add_i32 s39, s90, 0x8000
	s_add_i32 s18, s90, 0xa000
	v_writelane_b32 v254, s31, 38
	v_writelane_b32 v254, s88, 39
	s_add_i32 s40, s90, 0xc000
	s_add_i32 s41, s90, 0xe000
	v_writelane_b32 v254, s89, 40
	v_writelane_b32 v254, s29, 41
	v_writelane_b32 v254, s34, 42
	v_writelane_b32 v254, s35, 43
	v_writelane_b32 v254, s17, 44
	v_writelane_b32 v254, s38, 45
	v_writelane_b32 v254, s39, 46
	v_writelane_b32 v254, s18, 47
	v_writelane_b32 v254, s40, 48
	s_add_i32 s43, s90, 0x4000
	v_writelane_b32 v254, s41, 49
	v_mov_b32_e32 v1, v0
	v_mov_b32_e32 v2, v0
	v_mov_b32_e32 v3, v0
	s_movk_i32 s36, 0x3800
	s_mov_b64 s[14:15], 0x1800
	s_movk_i32 s16, 0x1000
	s_movk_i32 s37, 0x1c00
	s_mov_b64 s[96:97], 0x80
	s_movk_i32 s67, 0xe0
	s_movk_i32 s73, 0x60
	s_movk_i32 s74, 0x80
	s_movk_i32 s75, 0xa0
	s_movk_i32 s79, 0xc0
	s_mov_b64 s[92:93], 0x3000
	s_mov_b32 s42, 0x800000
	v_mov_b32_e32 v186, 0xe0
	s_mov_b32 s44, s95
	s_mov_b32 s101, 0
	s_mov_b32 s98, 0
	s_mov_b32 s99, 0x89abcdef
	v_writelane_b32 v254, s43, 50
	s_branch .LBB0_565
